# attention: lane^16 / lane^32 shuffles of the stick-breaking product via v_permlane16/32_swap instead of ds_bpermute (bit-identical)
# baseline (speedup 1.0000x reference)
; __device__ __forceinline__ void attn_unit(LAS unsigned char* lds, const bf16* P, bf16* Y, const float* gq, const float* gk, int b, int h, int qb, int tid, int wid, int lane, ...
;     ...
;                             const float x2 = r[3], x1 = x2 * r[2], x0 = x1 * r[1], T = x0 * r[0];
;                             const float A_ = __shfl_xor(T, 16), Bp = T * A_, Cc = __shfl_xor(Bp, 32);
;                             const float Xq = quad == 3 ? 1.0f : (quad == 2 ? A_ : (quad == 1 ? Cc : A_ * Cc));
;                             const float Yv = Xq * R;
;                             av[u][3] = be[3] * Yv; av[u][2] = be[2] * (x2 * Yv); av[u][1] = be[1] * (x1 * Yv); av[u][0] = be[0] * (x0 * Yv);
;                             R *= Bp * Cc;
.LBB0_335:
	v_mul_f32_e32 v47, v45, v44
	v_mul_f32_e32 v46, v49, v47
	v_mul_f32_e32 v44, v48, v46
	v_mov_b32_e32 v48, v44
	s_nop 1
	v_permlane16_swap_b32_e32 v44, v48
	v_cmp_gt_i32_e32 vcc, 3, v97
	v_mov_b32_e32 v49, 1.0
	s_waitcnt lgkmcnt(0)
	v_mul_f32_e32 v44, v44, v48
	v_mov_b32_e32 v50, v44
	s_nop 1
	v_permlane32_swap_b32_e32 v44, v50
	s_and_saveexec_b64 s[10:11], vcc
	s_cbranch_execz .LBB0_341
	v_cmp_ne_u32_e32 vcc, 2, v97
	s_and_saveexec_b64 s[12:13], vcc
	s_xor_b64 s[12:13], exec, s[12:13]
	s_cbranch_execz .LBB0_338
	s_waitcnt lgkmcnt(0)
	v_mul_f32_e32 v48, v48, v50
	v_cndmask_b32_e64 v49, v48, v50, s[6:7]

; __device__ __forceinline__ void attn_unit(LAS unsigned char* lds, const bf16* P, bf16* Y, const float* gq, const float* gk, int b, int h, int qb, int tid, int wid, int lane, ...
;     ...
;                             const float x2 = r[3], x1 = x2 * r[2], x0 = x1 * r[1], T = x0 * r[0];
;                             const float A_ = __shfl_xor(T, 16), Bp = T * A_, Cc = __shfl_xor(Bp, 32);
;                             const float Xq = quad == 3 ? 1.0f : (quad == 2 ? A_ : (quad == 1 ? Cc : A_ * Cc));
;                             const float Yv = Xq * R;
;                             av[u][3] = be[3] * Yv; av[u][2] = be[2] * (x2 * Yv); av[u][1] = be[1] * (x1 * Yv); av[u][0] = be[0] * (x0 * Yv);
;                             R *= Bp * Cc;
.LBB0_346:
	v_mul_f32_e32 v44, v45, v44
	v_mul_f32_e32 v51, v51, v44
	v_mul_f32_e32 v50, v50, v51
	v_mov_b32_e32 v52, v50
	s_nop 1
	v_permlane16_swap_b32_e32 v50, v52
	v_cmp_gt_i32_e32 vcc, 3, v97
	s_waitcnt lgkmcnt(0)
	v_mul_f32_e32 v70, v50, v52
	v_mov_b32_e32 v71, v70
	s_nop 1
	v_permlane32_swap_b32_e32 v70, v71
	v_mov_b32_e32 v50, 1.0
	s_and_saveexec_b64 s[10:11], vcc
	s_cbranch_execz .LBB0_352
	v_cmp_ne_u32_e32 vcc, 2, v97
	s_and_saveexec_b64 s[12:13], vcc
	s_xor_b64 s[12:13], exec, s[12:13]
	s_cbranch_execz .LBB0_349
	s_waitcnt lgkmcnt(0)
	v_mul_f32_e32 v50, v52, v71
	v_cndmask_b32_e64 v50, v50, v71, s[6:7]

; __device__ __forceinline__ void attn_unit(LAS unsigned char* lds, const bf16* P, bf16* Y, const float* gq, const float* gk, int b, int h, int qb, int tid, int wid, int lane, ...
;     ...
;                             const float x2 = r[3], x1 = x2 * r[2], x0 = x1 * r[1], T = x0 * r[0];
;                             const float A_ = __shfl_xor(T, 16), Bp = T * A_, Cc = __shfl_xor(Bp, 32);
;                             const float Xq = quad == 3 ? 1.0f : (quad == 2 ? A_ : (quad == 1 ? Cc : A_ * Cc));
;                             const float Yv = Xq * R;
;                             av[u][3] = be[3] * Yv; av[u][2] = be[2] * (x2 * Yv); av[u][1] = be[1] * (x1 * Yv); av[u][0] = be[0] * (x0 * Yv);
;                             R *= Bp * Cc;
.LBB0_356:
	v_mul_f32_e32 v77, v75, v74
	v_mul_f32_e32 v76, v79, v77
	v_mul_f32_e32 v69, v78, v76
	v_mov_b32_e32 v79, v69
	s_nop 1
	v_permlane16_swap_b32_e32 v69, v79
	v_cmp_gt_i32_e32 vcc, 3, v97
	v_mov_b32_e32 v78, 1.0
	s_waitcnt lgkmcnt(0)
	v_mul_f32_e32 v69, v69, v79
	v_mov_b32_e32 v74, v69
	s_nop 1
	v_permlane32_swap_b32_e32 v69, v74
	s_and_saveexec_b64 s[10:11], vcc
	s_cbranch_execz .LBB0_362
	v_cmp_ne_u32_e32 vcc, 2, v97
	s_and_saveexec_b64 s[12:13], vcc
	s_xor_b64 s[12:13], exec, s[12:13]
	s_cbranch_execz .LBB0_359
	s_waitcnt lgkmcnt(0)
	v_mul_f32_e32 v78, v79, v74
	v_cndmask_b32_e64 v78, v78, v74, s[6:7]

; __device__ __forceinline__ void attn_unit(LAS unsigned char* lds, const bf16* P, bf16* Y, const float* gq, const float* gk, int b, int h, int qb, int tid, int wid, int lane, ...
;     ...
;                             const float x2 = r[3], x1 = x2 * r[2], x0 = x1 * r[1], T = x0 * r[0];
;                             const float A_ = __shfl_xor(T, 16), Bp = T * A_, Cc = __shfl_xor(Bp, 32);
;                             const float Xq = quad == 3 ? 1.0f : (quad == 2 ? A_ : (quad == 1 ? Cc : A_ * Cc));
;                             const float Yv = Xq * R;
;                             av[u][3] = be[3] * Yv; av[u][2] = be[2] * (x2 * Yv); av[u][1] = be[1] * (x1 * Yv); av[u][0] = be[0] * (x0 * Yv);
;                             R *= Bp * Cc;
.LBB0_366:
	v_mul_f32_e32 v82, v75, v74
	v_mul_f32_e32 v81, v81, v82
	v_mul_f32_e32 v69, v80, v81
	v_mov_b32_e32 v83, v69
	s_nop 1
	v_permlane16_swap_b32_e32 v69, v83
	v_cmp_gt_i32_e32 vcc, 3, v97
	v_mov_b32_e32 v80, 1.0
	s_waitcnt lgkmcnt(0)
	v_mul_f32_e32 v69, v69, v83
	v_mov_b32_e32 v74, v69
	s_nop 1
	v_permlane32_swap_b32_e32 v69, v74
	s_and_saveexec_b64 s[10:11], vcc
	s_cbranch_execz .LBB0_372
	v_cmp_ne_u32_e32 vcc, 2, v97
	s_and_saveexec_b64 s[12:13], vcc
	s_xor_b64 s[12:13], exec, s[12:13]
	s_cbranch_execz .LBB0_369
	s_waitcnt lgkmcnt(0)
	v_mul_f32_e32 v80, v83, v74
	v_cndmask_b32_e64 v80, v80, v74, s[6:7]

; __device__ __forceinline__ void attn_unit(LAS unsigned char* lds, const bf16* P, bf16* Y, const float* gq, const float* gk, int b, int h, int qb, int tid, int wid, int lane, ...
;     ...
;                             const float x2 = r[3], x1 = x2 * r[2], x0 = x1 * r[1], T = x0 * r[0];
;                             const float A_ = __shfl_xor(T, 16), Bp = T * A_, Cc = __shfl_xor(Bp, 32);
;                             const float Xq = quad == 3 ? 1.0f : (quad == 2 ? A_ : (quad == 1 ? Cc : A_ * Cc));
;                             const float Yv = Xq * R;
;                             av[u][3] = be[3] * Yv; av[u][2] = be[2] * (x2 * Yv); av[u][1] = be[1] * (x1 * Yv); av[u][0] = be[0] * (x0 * Yv);
;                             R *= Bp * Cc;
.LBB0_390:
	v_mul_f32_e32 v65, v57, v56
	v_mul_f32_e32 v64, v63, v65
	v_mul_f32_e32 v56, v62, v64
	v_mov_b32_e32 v66, v56
	s_nop 1
	v_permlane16_swap_b32_e32 v56, v66
	v_cmp_gt_i32_e32 vcc, 3, v97
	s_waitcnt lgkmcnt(0)
	v_mul_f32_e32 v62, v56, v66
	v_mov_b32_e32 v63, v62
	s_nop 1
	v_permlane32_swap_b32_e32 v62, v63
	v_mov_b32_e32 v56, 1.0
	s_and_saveexec_b64 s[10:11], vcc
	s_cbranch_execz .LBB0_396
	v_cmp_ne_u32_e32 vcc, 2, v97
	s_and_saveexec_b64 s[12:13], vcc
	s_xor_b64 s[12:13], exec, s[12:13]
	s_cbranch_execz .LBB0_393
	s_waitcnt lgkmcnt(0)
	v_mul_f32_e32 v56, v66, v63
	v_cndmask_b32_e64 v56, v56, v63, s[6:7]

; __device__ __forceinline__ void attn_unit(LAS unsigned char* lds, const bf16* P, bf16* Y, const float* gq, const float* gk, int b, int h, int qb, int tid, int wid, int lane, ...
;     ...
;                             const float x2 = r[3], x1 = x2 * r[2], x0 = x1 * r[1], T = x0 * r[0];
;                             const float A_ = __shfl_xor(T, 16), Bp = T * A_, Cc = __shfl_xor(Bp, 32);
;                             const float Xq = quad == 3 ? 1.0f : (quad == 2 ? A_ : (quad == 1 ? Cc : A_ * Cc));
;                             const float Yv = Xq * R;
;                             av[u][3] = be[3] * Yv; av[u][2] = be[2] * (x2 * Yv); av[u][1] = be[1] * (x1 * Yv); av[u][0] = be[0] * (x0 * Yv);
;                             R *= Bp * Cc;
.LBB0_400:
	v_mul_f32_e32 v60, v61, v60
	v_mul_f32_e32 v67, v67, v60
	v_mul_f32_e32 v66, v66, v67
	v_mov_b32_e32 v86, v66
	s_nop 1
	v_permlane16_swap_b32_e32 v66, v86
	v_cmp_gt_i32_e32 vcc, 3, v97
	s_waitcnt lgkmcnt(0)
	v_mul_f32_e32 v84, v66, v86
	v_mov_b32_e32 v85, v84
	s_nop 1
	v_permlane32_swap_b32_e32 v84, v85
	v_mov_b32_e32 v66, 1.0
	s_and_saveexec_b64 s[10:11], vcc
	s_cbranch_execz .LBB0_406
	v_cmp_ne_u32_e32 vcc, 2, v97
	s_and_saveexec_b64 s[12:13], vcc
	s_xor_b64 s[12:13], exec, s[12:13]
	s_cbranch_execz .LBB0_403
	s_waitcnt lgkmcnt(0)
	v_mul_f32_e32 v66, v86, v85
	v_cndmask_b32_e64 v66, v66, v85, s[6:7]

; __device__ __forceinline__ void attn_unit(LAS unsigned char* lds, const bf16* P, bf16* Y, const float* gq, const float* gk, int b, int h, int qb, int tid, int wid, int lane, ...
;     ...
;                             const float x2 = r[3], x1 = x2 * r[2], x0 = x1 * r[1], T = x0 * r[0];
;                             const float A_ = __shfl_xor(T, 16), Bp = T * A_, Cc = __shfl_xor(Bp, 32);
;                             const float Xq = quad == 3 ? 1.0f : (quad == 2 ? A_ : (quad == 1 ? Cc : A_ * Cc));
;                             const float Yv = Xq * R;
;                             av[u][3] = be[3] * Yv; av[u][2] = be[2] * (x2 * Yv); av[u][1] = be[1] * (x1 * Yv); av[u][0] = be[0] * (x0 * Yv);
;                             R *= Bp * Cc;
.LBB0_463:
	v_mul_f32_e32 v84, v61, v60
	v_mul_f32_e32 v67, v67, v84
	v_mul_f32_e32 v60, v66, v67
	v_mov_b32_e32 v86, v60
	s_nop 1
	v_permlane16_swap_b32_e32 v60, v86
	v_cmp_gt_i32_e32 vcc, 3, v97
	v_mov_b32_e32 v85, 1.0
	s_waitcnt lgkmcnt(0)
	v_mul_f32_e32 v60, v60, v86
	v_mov_b32_e32 v66, v60
	s_nop 1
	v_permlane32_swap_b32_e32 v60, v66
	s_and_saveexec_b64 s[10:11], vcc
	s_cbranch_execz .LBB0_469
	v_cmp_ne_u32_e32 vcc, 2, v97
	s_and_saveexec_b64 s[12:13], vcc
	s_xor_b64 s[12:13], exec, s[12:13]
	s_cbranch_execz .LBB0_466
	s_waitcnt lgkmcnt(0)
	v_mul_f32_e32 v85, v86, v66
	v_cndmask_b32_e64 v85, v85, v66, s[6:7]
